# P8 meta-row tasks moved to phase end with ticket queue; attention max tree shortened; skinny loads batched
# speedup vs baseline: 1.0050x; 1.0050x over previous
; __device__ __forceinline__ void attn_unit(const bf16* __restrict__ QB, const bf16* __restrict__ KB, const bf16* __restrict__ VB, bf16* __restrict__ YATT, ...
;     ...
;             float mx = fmaxf(s0[0], s1[0]);
; #pragma unroll
;             for (int r = 1; r < 16; ++r) mx = fmaxf(mx, fmaxf(s0[r], s1[r]));
;             { auto rr = __builtin_amdgcn_permlane32_swap(__float_as_uint(mx), __float_as_uint(mx), false, false); mx = fmaxf(__uint_as_float(rr[0]), __uint_as_float(rr[1])); }
;             const bool need = (j == jsw) || (mx > THR);
;             if (__any(need)) {
;                 const float delta = need ? mx : 0.f;
;                 const float alpha = (j == jsw) ? 1.f : __builtin_amdgcn_exp2f(-delta);
;                 lrun *= alpha;
; #pragma unroll
;                 for (int r = 0; r < 16; ++r) { s0[r] -= delta; s1[r] -= delta; negc[r] -= delta; }
; #pragma unroll
;                 for (int e = 0; e < 4; ++e)
; #pragma unroll
;                     for (int r = 0; r < 16; ++r) acc[e][r] *= alpha;
;             }
.LBB0_577:
	s_or_b64 exec, exec, s[78:79]
	s_nop 8
	v_max3_f32 v2, v98, v99, v100
	v_max3_f32 v3, v101, v102, v103
	v_max3_f32 v4, v104, v105, v106
	v_max3_f32 v6, v107, v108, v109
	v_max3_f32 v2, v2, v110, v111
	v_max3_f32 v3, v3, v112, v113
	v_max3_f32 v4, v4, v114, v115
	v_max3_f32 v6, v6, v116, v117
	v_max3_f32 v2, v2, v118, v119
	v_max3_f32 v3, v3, v120, v121
	v_max3_f32 v4, v4, v122, v123
	v_max3_f32 v6, v6, v124, v125
	v_max3_f32 v2, v2, v126, v127
	v_max3_f32 v3, v3, v128, v129
	v_max3_f32 v2, v2, v3, v4
	v_max_f32_e32 v2, v2, v6
	v_mov_b32_e32 v3, v2
	s_nop 1
	v_permlane32_swap_b32_e32 v2, v3
	v_max_f32_e32 v3, v3, v3
	v_max_f32_e32 v2, v2, v2
	v_max_f32_e32 v2, v2, v3
	s_mov_b32 s10, 0x42700000
	v_cmp_eq_u32_e64 s[8:9], s81, v206
	v_cmp_lt_f32_e32 vcc, s10, v2
	s_or_b64 vcc, s[8:9], vcc
	s_cbranch_vccz .LBB0_579
	v_cndmask_b32_e32 v2, 0, v2, vcc
	v_exp_f32_e64 v3, -v2
	v_sub_f32_e32 v97, v97, v2
	v_sub_f32_e32 v96, v96, v2
	v_sub_f32_e32 v95, v95, v2
	v_cndmask_b32_e64 v4, v3, 1.0, s[8:9]
	v_pk_add_f32 v[114:115], v[114:115], v[2:3] op_sel_hi:[1,0] neg_lo:[0,1] neg_hi:[0,1]
	v_pk_add_f32 v[98:99], v[98:99], v[2:3] op_sel_hi:[1,0] neg_lo:[0,1] neg_hi:[0,1]
	v_pk_add_f32 v[116:117], v[116:117], v[2:3] op_sel_hi:[1,0] neg_lo:[0,1] neg_hi:[0,1]
	v_pk_add_f32 v[100:101], v[100:101], v[2:3] op_sel_hi:[1,0] neg_lo:[0,1] neg_hi:[0,1]
	v_pk_add_f32 v[118:119], v[118:119], v[2:3] op_sel_hi:[1,0] neg_lo:[0,1] neg_hi:[0,1]
	v_pk_add_f32 v[102:103], v[102:103], v[2:3] op_sel_hi:[1,0] neg_lo:[0,1] neg_hi:[0,1]
	v_pk_add_f32 v[120:121], v[120:121], v[2:3] op_sel_hi:[1,0] neg_lo:[0,1] neg_hi:[0,1]
	v_pk_add_f32 v[104:105], v[104:105], v[2:3] op_sel_hi:[1,0] neg_lo:[0,1] neg_hi:[0,1]
	v_pk_add_f32 v[122:123], v[122:123], v[2:3] op_sel_hi:[1,0] neg_lo:[0,1] neg_hi:[0,1]
	v_pk_add_f32 v[106:107], v[106:107], v[2:3] op_sel_hi:[1,0] neg_lo:[0,1] neg_hi:[0,1]
	v_pk_add_f32 v[124:125], v[124:125], v[2:3] op_sel_hi:[1,0] neg_lo:[0,1] neg_hi:[0,1]
	v_pk_add_f32 v[108:109], v[108:109], v[2:3] op_sel_hi:[1,0] neg_lo:[0,1] neg_hi:[0,1]
	v_pk_add_f32 v[126:127], v[126:127], v[2:3] op_sel_hi:[1,0] neg_lo:[0,1] neg_hi:[0,1]
	v_pk_add_f32 v[110:111], v[110:111], v[2:3] op_sel_hi:[1,0] neg_lo:[0,1] neg_hi:[0,1]
	v_pk_add_f32 v[128:129], v[128:129], v[2:3] op_sel_hi:[1,0] neg_lo:[0,1] neg_hi:[0,1]
	v_pk_add_f32 v[112:113], v[112:113], v[2:3] op_sel_hi:[1,0] neg_lo:[0,1] neg_hi:[0,1]
	v_sub_f32_e32 v94, v94, v2
	v_sub_f32_e32 v93, v93, v2
	v_sub_f32_e32 v92, v92, v2
	v_sub_f32_e32 v91, v91, v2
	v_sub_f32_e32 v90, v90, v2
	v_sub_f32_e32 v89, v89, v2
	v_sub_f32_e32 v88, v88, v2
	v_sub_f32_e32 v87, v87, v2
	v_sub_f32_e32 v86, v86, v2
	v_sub_f32_e32 v85, v85, v2
	v_sub_f32_e32 v84, v84, v2
	v_sub_f32_e32 v83, v83, v2
	v_sub_f32_e32 v82, v82, v2
	v_pk_mul_f32 v[80:81], v[80:81], v[4:5] op_sel_hi:[1,0]
	v_pk_mul_f32 v[78:79], v[78:79], v[4:5] op_sel_hi:[1,0]
	v_pk_mul_f32 v[76:77], v[76:77], v[4:5] op_sel_hi:[1,0]
	v_pk_mul_f32 v[74:75], v[74:75], v[4:5] op_sel_hi:[1,0]
	v_pk_mul_f32 v[72:73], v[72:73], v[4:5] op_sel_hi:[1,0]
	v_pk_mul_f32 v[70:71], v[70:71], v[4:5] op_sel_hi:[1,0]
	v_pk_mul_f32 v[68:69], v[68:69], v[4:5] op_sel_hi:[1,0]
	v_pk_mul_f32 v[66:67], v[66:67], v[4:5] op_sel_hi:[1,0]
	v_pk_mul_f32 v[64:65], v[64:65], v[4:5] op_sel_hi:[1,0]
	v_pk_mul_f32 v[62:63], v[62:63], v[4:5] op_sel_hi:[1,0]
	v_pk_mul_f32 v[60:61], v[60:61], v[4:5] op_sel_hi:[1,0]
	v_pk_mul_f32 v[58:59], v[58:59], v[4:5] op_sel_hi:[1,0]
	v_pk_mul_f32 v[56:57], v[56:57], v[4:5] op_sel_hi:[1,0]
	v_pk_mul_f32 v[54:55], v[54:55], v[4:5] op_sel_hi:[1,0]
	v_pk_mul_f32 v[52:53], v[52:53], v[4:5] op_sel_hi:[1,0]
	v_pk_mul_f32 v[50:51], v[50:51], v[4:5] op_sel_hi:[1,0]
	v_pk_mul_f32 v[48:49], v[48:49], v[4:5] op_sel_hi:[1,0]
	v_pk_mul_f32 v[46:47], v[46:47], v[4:5] op_sel_hi:[1,0]
	v_pk_mul_f32 v[44:45], v[44:45], v[4:5] op_sel_hi:[1,0]
	v_pk_mul_f32 v[42:43], v[42:43], v[4:5] op_sel_hi:[1,0]
	v_pk_mul_f32 v[40:41], v[40:41], v[4:5] op_sel_hi:[1,0]
	v_pk_mul_f32 v[38:39], v[38:39], v[4:5] op_sel_hi:[1,0]
	v_pk_mul_f32 v[36:37], v[36:37], v[4:5] op_sel_hi:[1,0]
	v_pk_mul_f32 v[34:35], v[34:35], v[4:5] op_sel_hi:[1,0]
	v_pk_mul_f32 v[32:33], v[32:33], v[4:5] op_sel_hi:[1,0]
	v_pk_mul_f32 v[30:31], v[30:31], v[4:5] op_sel_hi:[1,0]
	v_pk_mul_f32 v[28:29], v[28:29], v[4:5] op_sel_hi:[1,0]
	v_pk_mul_f32 v[26:27], v[26:27], v[4:5] op_sel_hi:[1,0]
	v_pk_mul_f32 v[24:25], v[24:25], v[4:5] op_sel_hi:[1,0]
	v_pk_mul_f32 v[22:23], v[22:23], v[4:5] op_sel_hi:[1,0]
	v_pk_mul_f32 v[20:21], v[20:21], v[4:5] op_sel_hi:[1,0]
	v_pk_mul_f32 v[18:19], v[18:19], v[4:5] op_sel_hi:[1,0]
	v_mul_f32_e32 v207, v207, v4

; #define LAS __attribute__((address_space(3)))
; #define SS2 ((float*)(WSP() + WS_SS2))
; #define AM ((float*)(WSP() + WS_AM))
; __global__ void __launch_bounds__(NWAVES * 64, 2) hybrid_fwd(Params P) {
;     ...
;     if (IN(8)) {
;         FUpMeta fm{SS2, AM};
;         skinny16(H1B + (size_t)MAINR * 1024, 1024, WUP, 1024, UPC, 1024, bx, G, lane, wave, (LAS float*)lds, fm);
.LBB0_1171:
.LBB0_1172:
	s_cmp_lt_i32 s78, 9
	s_cselect_b64 s[6:7], -1, 0
	s_and_b64 s[14:15], s[6:7], s[4:5]
	s_andn2_b64 vcc, exec, s[14:15]
	s_cbranch_vccnz .LBB0_1235
	s_branch .LBB0_1181

; #define LAS __attribute__((address_space(3)))
; #define SS2 ((float*)(WSP() + WS_SS2))
; #define AM ((float*)(WSP() + WS_AM))
; template <class F> __device__ __forceinline__ void skinny_task(const bf16* A16, int lda, const bf16* Bt, int ldb, int K, int pn, int wc, int lane, int wave, LAS float* red, int rowbase, int clbase, const F& f) {
;     const int fr = lane & 15, fq = lane >> 4;
;     typename F::Pre pre = f.load(rowbase + fr, clbase + 8 * fq);
;     f32x4 c00 = {0.f, 0.f, 0.f, 0.f}, c01 = c00, c10 = c00, c11 = c00;
;     const bf16* tb = Bt + (size_t)(pn * 256 + 32 * wc) * ldb + fq * 8;
;     const bf16* b00 = tb + (size_t)pg8::perm32(fr) * ldb; const bf16* b01 = tb + (size_t)pg8::perm32(16 + fr) * ldb;
;     const bf16* b10 = b00 + (size_t)128 * ldb; const bf16* b11 = b01 + (size_t)128 * ldb;
;     const bf16* ap = A16 + (size_t)fr * lda + fq * 8;
; #pragma unroll 4
;     for (int k0 = 32 * wave; k0 < K; k0 += 256) {
;         const bf16x8 a = *(const bf16x8*)(ap + k0);
;         const bf16x8 v00 = *(const bf16x8*)(b00 + k0), v01 = *(const bf16x8*)(b01 + k0), v10 = *(const bf16x8*)(b10 + k0), v11 = *(const bf16x8*)(b11 + k0);
;         c00 = __builtin_amdgcn_mfma_f32_16x16x32_bf16(v00, a, c00, 0, 0, 0); c01 = __builtin_amdgcn_mfma_f32_16x16x32_bf16(v01, a, c01, 0, 0, 0);
;         c10 = __builtin_amdgcn_mfma_f32_16x16x32_bf16(v10, a, c10, 0, 0, 0); c11 = __builtin_amdgcn_mfma_f32_16x16x32_bf16(v11, a, c11, 0, 0, 0);
;     }
;     LAS f32x4* R = (LAS f32x4*)red + (wave * 4) * 64 + lane;
;     R[0] = c00; R[64] = c01; R[128] = c10; R[192] = c11;
;     __syncthreads();
;     if (wave == 0) {
;         LAS const f32x4* S = (LAS const f32x4*)red + lane;
; #pragma unroll
;         for (int w = 1; w < 8; ++w) { c00 += S[(w * 4) * 64]; c01 += S[(w * 4 + 1) * 64]; c10 += S[(w * 4 + 2) * 64]; c11 += S[(w * 4 + 3) * 64]; }
;         f.apply(rowbase + fr, clbase + 8 * fq, pre, c00, c01, c10, c11);
;     }
;     __syncthreads();
; }
;     asm volatile("" : "+v"(lane));
;     for (int t = (bx - boff + G) % G; t < N / 64; t += G) skinny_task(A16, lda, Bt, ldb, K, t >> 2, t & 3, lane, wave, red, MAINR, t * 64, f);
; }
; __global__ void __launch_bounds__(NWAVES * 64, 2) hybrid_fwd(Params P) {
;     ...
;     if (IN(8)) {
;         FUpMeta fm{SS2, AM};
;         skinny16(H1B + (size_t)MAINR * 1024, 1024, WUP, 1024, UPC, 1024, bx, G, lane, wave, (LAS float*)lds, fm);
.Lsk_P8_begin:
	v_mbcnt_lo_u32_b32 v174, -1, 0
	v_mbcnt_hi_u32_b32 v174, -1, v174
	s_abs_i32 s12, s3
	v_cvt_f32_u32_e32 v0, s12
	s_sub_i32 s16, 0, s12
	s_add_i32 s13, s3, s2
	s_ashr_i32 s18, s13, 31
	v_rcp_iflag_f32_e32 v0, v0
	s_abs_i32 s13, s13
	s_mov_b64 s[4:5], s[0:1]
	s_mov_b64 s[6:7], s[0:1]
	v_mul_f32_e32 v0, 0x4f7ffffe, v0
	v_cvt_u32_f32_e32 v0, v0
	s_mov_b64 s[8:9], s[0:1]
	s_mov_b64 s[10:11], s[0:1]
	v_readfirstlane_b32 s17, v0
	s_mul_i32 s16, s16, s17
	s_mul_hi_u32 s16, s17, s16
	s_add_i32 s17, s17, s16
	s_mul_hi_u32 s16, s13, s17
	s_mul_i32 s16, s16, s12
	s_sub_i32 s13, s13, s16
	s_sub_i32 s16, s13, s12
	s_cmp_ge_u32 s13, s12
	s_cselect_b32 s13, s16, s13
	s_sub_i32 s16, s13, s12
	s_cmp_ge_u32 s13, s12
	s_cselect_b32 s12, s16, s13
	s_xor_b32 s19, s12, s18
	s_sub_i32 s12, s19, s18
	v_readlane_b32 s98, v240, 3
	s_load_dwordx2 s[100:101], s[0:1], 0xf0
	s_nop 2
	s_cmp_lg_u32 s98, 0
	s_cbranch_scc1 .Ltk_P8a
	s_mov_b64 s[98:99], exec
	s_mov_b64 exec, 1
	v_mov_b32_e32 v244, 1
	v_mov_b32_e32 v245, 0x83e84
	s_waitcnt lgkmcnt(0)
	global_atomic_add v244, v245, v244, s[100:101] sc0
	s_waitcnt vmcnt(0)
	v_mov_b32_e32 v245, 0x20200
	ds_write_b32 v245, v244
	s_mov_b64 exec, s[98:99]
.Ltk_P8a:
	s_waitcnt lgkmcnt(0)
	s_barrier
	v_mov_b32_e32 v245, 0x20200
	ds_read_b32 v244, v245
	s_waitcnt lgkmcnt(0)
	v_readfirstlane_b32 s12, v244
	s_nop 3
	s_barrier
	s_mov_b32 s19, s12
	s_mov_b32 s18, 0
	s_cmpk_gt_i32 s12, 0x57
	s_cbranch_scc1 .Lsk_P8_end
	s_waitcnt vmcnt(0)
	v_and_b32_e32 v4, 15, v174
	s_load_dwordx2 s[16:17], s[4:5], 0xf0
	s_load_dwordx2 s[20:21], s[6:7], 0xf0
	s_load_dwordx2 s[22:23], s[8:9], 0xf0
	s_load_dwordx2 s[24:25], s[10:11], 0xf0
	v_or_b32_e32 v0, 0x8000, v4
	s_mov_b32 s8, 0x800d
	v_readlane_b32 s11, v240, 0
	v_cmp_lt_u32_e32 vcc, s8, v0
	v_lshlrev_b32_e32 v0, 2, v0
	v_mov_b32_e32 v1, 0
	s_cmpk_lt_u32 s11, 0x800
	v_readlane_b32 s6, v240, 3
	s_waitcnt lgkmcnt(0)
	v_lshl_add_u64 v[2:3], s[16:17], 0, v[0:1]
	s_mov_b64 s[8:9], 0x21000
	s_cselect_b64 s[4:5], -1, 0
	s_lshl_b32 s10, s6, 5
	s_lshl_b32 s13, s6, 12
	v_lshl_add_u64 v[18:19], v[2:3], 0, s[8:9]
	v_add_u32_e32 v0, -14, v4
	s_movk_i32 s8, 0x2c00
	v_mov_b64_e32 v[2:3], s[20:21]
	s_cmp_lt_u32 s11, 64
	v_mad_u64_u32 v[2:3], s[8:9], v0, s8, v[2:3]
	v_and_b32_e32 v6, 3, v174
	s_cselect_b64 s[6:7], -1, 0
	s_mov_b64 s[8:9], 0x59000
	s_and_b64 s[6:7], s[6:7], vcc
	v_lshl_add_u64 v[20:21], v[2:3], 0, s[8:9]
	s_andn2_b32 s11, s11, 63
	v_lshlrev_b32_e32 v0, 12, v174
	v_lshlrev_b32_e32 v2, 11, v6
	s_mov_b32 s8, 0xc000
	v_and_or_b32 v0, v0, s8, v2
	s_add_u32 s8, s24, s11
	s_addc_u32 s9, s25, 0
	v_lshl_add_u64 v[24:25], s[8:9], 0, v[0:1]
	s_lshl_b32 s8, s19, 6
	s_lshl_b32 s9, s18, 6
	s_sub_i32 s16, s8, s9
	s_lshl_b32 s8, s19, 5
	s_lshl_b32 s9, s18, 5
	s_lshl_b32 s17, s3, 6
	s_sub_i32 s18, s8, s9
	s_lshl_b32 s19, s3, 5
	s_add_u32 s8, s22, s11
	v_ashrrev_i32_e32 v5, 1, v174
	v_lshlrev_b32_e32 v0, 11, v4
	s_addc_u32 s9, s23, 0
	v_and_b32_e32 v16, -8, v5
	v_lshl_add_u64 v[0:1], s[8:9], 0, v[0:1]
	s_mov_b64 s[8:9], 0xb300000
	v_ashrrev_i32_e32 v17, 31, v16
	v_lshl_add_u64 v[26:27], v[0:1], 0, s[8:9]
	v_cndmask_b32_e64 v0, 0, 1, s[4:5]
	v_lshl_add_u32 v32, v174, 4, 0
	v_and_b32_e32 v33, 24, v5
	v_lshlrev_b64 v[22:23], 1, v[16:17]
	s_add_i32 s20, s10, 0xffffff00
	v_cmp_ne_u32_e64 s[4:5], 1, v0
	s_mov_b32 s21, 0xd80000
	s_mov_b32 s22, 0xd82000
	s_mov_b32 s23, 0xdc0000
	s_mov_b32 s24, 0xdc2000
	s_mov_b64 s[8:9], 0x200
	v_mov_b32_e32 v17, 0x358637bd
	s_branch .LBB0_1176
.LBB0_1175:
	s_or_b64 exec, exec, s[10:11]
	v_readlane_b32 s98, v240, 3
	s_load_dwordx2 s[100:101], s[0:1], 0xf0
	s_nop 2
	s_cmp_lg_u32 s98, 0
	s_cbranch_scc1 .Ltk_P8b
	s_mov_b64 s[98:99], exec
	s_mov_b64 exec, 1
	v_mov_b32_e32 v244, 1
	v_mov_b32_e32 v245, 0x83e84
	s_waitcnt lgkmcnt(0)
	global_atomic_add v244, v245, v244, s[100:101] sc0
	s_waitcnt vmcnt(0)
	v_mov_b32_e32 v245, 0x20200
	ds_write_b32 v245, v244
	s_mov_b64 exec, s[98:99]
.Ltk_P8b:
	s_waitcnt lgkmcnt(0)
	s_barrier
	v_mov_b32_e32 v245, 0x20200
	ds_read_b32 v244, v245
	s_waitcnt lgkmcnt(0)
	v_readfirstlane_b32 s12, v244
	s_nop 3
	s_barrier
	s_lshl_b32 s16, s12, 6
	s_lshl_b32 s18, s12, 5
	s_cmpk_lt_i32 s12, 0x58
	s_cbranch_scc0 .Lsk_P8_end

; __device__ __forceinline__ unsigned xb_ld(unsigned* p)              { return __hip_atomic_load(p, __ATOMIC_RELAXED, __HIP_MEMORY_SCOPE_AGENT); }
; __device__ __forceinline__ unsigned xb_add(unsigned* p, unsigned v) { return __hip_atomic_fetch_add(p, v, __ATOMIC_RELAXED, __HIP_MEMORY_SCOPE_AGENT); }
; __device__ __forceinline__ void xcd_barrier_complete(unsigned* bar, unsigned x, unsigned& nloc, unsigned& nx) {
;     const unsigned G = gridDim.x * gridDim.y * gridDim.z;
;     unsigned sum, cnt, mine, sp = 0u;
;     for (;;) {
;         sum = 0u; cnt = 0u; mine = 0u;
; #pragma unroll
;         for (unsigned j = 0; j < 16; ++j) { const unsigned c = xb_ld(&bar[XB_XCNT(j)]); sum += c; cnt += (c > 0u) ? 1u : 0u; mine = (j == x) ? c : mine; }
;         if (sum == G) break;
;         __builtin_amdgcn_s_sleep(1);
;         if ((++sp & 255u) == 0u) { if (xb_ld(&bar[XB_TMO])) break; if (sp > XB_SPIN_CAP) { atomicAdd(&bar[XB_TMO], 1u); break; } }
;     }
;     nloc = mine > 0u ? mine : 1u; nx = cnt > 0u ? cnt : 1u;
; }
; __device__ __forceinline__ void xcd_barrier(const XcdBarrier& b) {
;     asm volatile("s_waitcnt vmcnt(0)" ::: "memory");
;     __syncthreads();
;     if (threadIdx.x == 0) {
;         unsigned* bar = b.bar;
;         __builtin_amdgcn_s_waitcnt(0);
;         unsigned nloc = b.st[0], nx = b.st[1];
;         if (nloc == 0u) { xcd_barrier_complete(bar, b.x, nloc, nx); b.st[0] = nloc; b.st[1] = nx; }
;         const unsigned old = xb_add(&bar[XB_XSUB(b.x)], 1u);
; __global__ void __launch_bounds__(NWAVES * 64, 2) hybrid_fwd(Params P) {
;     ...
;     do { if (IN(8) && IN(10)) xcd_barrier(xbar); } while (0);
;     if (IN(10)) {
.Lsk_P8_end:
.LBB0_1235:
	s_cmp_gt_i32 s79, 10
	s_cselect_b64 s[4:5], -1, 0
	s_and_b64 s[6:7], s[14:15], s[4:5]
	s_andn2_b64 vcc, exec, s[6:7]
	s_cbranch_vccnz .LBB0_1289
	s_waitcnt vmcnt(0)
	s_waitcnt vmcnt(0)
	s_barrier
	s_mov_b64 s[6:7], exec
	v_readlane_b32 s8, v240, 1
	v_readlane_b32 s9, v240, 2
	s_and_b64 s[8:9], s[6:7], s[8:9]
	s_mov_b64 exec, s[8:9]
	s_cbranch_execz .LBB0_1288
	s_add_i32 s8, 0, 0x20000
	v_mov_b32_e32 v0, s8
	s_waitcnt vmcnt(0) expcnt(0) lgkmcnt(0)
	ds_read_b32 v2, v0
	s_add_i32 s8, 0, 0x20004
	v_mov_b32_e32 v0, s8
	ds_read_b32 v0, v0
	s_waitcnt lgkmcnt(1)
	v_cmp_ne_u32_e32 vcc, 0, v2
	s_cbranch_vccnz .LBB0_1252
	s_load_dwordx2 s[12:13], s[84:85], 0x4
	s_add_u32 s8, s80, 0x80200
	s_addc_u32 s9, s81, 0
	s_add_u32 s10, s80, 0x80400
	s_addc_u32 s11, s81, 0
	s_waitcnt lgkmcnt(0)
	s_mul_i32 s33, s12, s3
	s_add_u32 s12, s80, 0x80500
	s_mul_i32 s33, s33, s13
	s_addc_u32 s13, s81, 0
	s_add_u32 s14, s80, 0x80600
	s_addc_u32 s15, s81, 0
	s_add_u32 s16, s80, 0x80700
	s_addc_u32 s17, s81, 0
	s_add_u32 s18, s80, 0x80800
	s_addc_u32 s19, s81, 0
	s_add_u32 s20, s80, 0x80900
	s_addc_u32 s21, s81, 0
	s_add_u32 s22, s80, 0x80a00
	s_addc_u32 s23, s81, 0
	s_add_u32 s24, s80, 0x80b00
	s_addc_u32 s25, s81, 0
	s_add_u32 s26, s80, 0x80c00
	s_addc_u32 s27, s81, 0
	s_add_u32 s28, s80, 0x80d00
	s_addc_u32 s29, s81, 0
	s_add_u32 s30, s80, 0x80e00
	s_addc_u32 s31, s81, 0
	s_add_u32 s34, s80, 0x80f00
	s_addc_u32 s35, s81, 0
	s_add_u32 s36, s80, 0x81000
	s_addc_u32 s37, s81, 0
	s_add_u32 s38, s80, 0x81100
	s_addc_u32 s39, s81, 0
	s_add_u32 s40, s80, 0x81200
	s_addc_u32 s41, s81, 0
	s_add_u32 s42, s80, 0x81300
	s_addc_u32 s43, s81, 0
	s_mov_b32 s50, 1
	v_mov_b32_e32 v16, 0
	s_branch .LBB0_1240

; __global__ void __launch_bounds__(NWAVES * 64, 2) hybrid_fwd(Params P) {
	.amdhsa_kernel _Z10hybrid_fwd6Params
		.amdhsa_group_segment_fixed_size 0
		.amdhsa_private_segment_fixed_size 0
		.amdhsa_kernarg_size 512
		.amdhsa_user_sgpr_count 2
		.amdhsa_user_sgpr_dispatch_ptr 0
		.amdhsa_user_sgpr_queue_ptr 0
		.amdhsa_user_sgpr_kernarg_segment_ptr 1
		.amdhsa_user_sgpr_dispatch_id 0
		.amdhsa_user_sgpr_kernarg_preload_length 0
		.amdhsa_user_sgpr_kernarg_preload_offset 0
		.amdhsa_user_sgpr_private_segment_size 0
		.amdhsa_uses_dynamic_stack 0
		.amdhsa_enable_private_segment 0
		.amdhsa_system_sgpr_workgroup_id_x 1
		.amdhsa_system_sgpr_workgroup_id_y 0
		.amdhsa_system_sgpr_workgroup_id_z 0
		.amdhsa_system_sgpr_workgroup_info 0
		.amdhsa_system_vgpr_workitem_id 2
		.amdhsa_next_free_vgpr 248
		.amdhsa_next_free_sgpr 102
		.amdhsa_accum_offset 248
		.amdhsa_reserve_vcc 1
		.amdhsa_float_round_mode_32 0
		.amdhsa_float_round_mode_16_64 0
		.amdhsa_float_denorm_mode_32 3
		.amdhsa_float_denorm_mode_16_64 3
		.amdhsa_dx10_clamp 1
		.amdhsa_ieee_mode 1
		.amdhsa_fp16_overflow 0
		.amdhsa_tg_split 0
		.amdhsa_exception_fp_ieee_invalid_op 0
		.amdhsa_exception_fp_denorm_src 0
		.amdhsa_exception_fp_ieee_div_zero 0
		.amdhsa_exception_fp_ieee_overflow 0
		.amdhsa_exception_fp_ieee_underflow 0
		.amdhsa_exception_fp_ieee_inexact 0
		.amdhsa_exception_int_div_zero 0
	.end_amdhsa_kernel

; __global__ void __launch_bounds__(NWAVES * 64, 2) hybrid_fwd(Params P) {
amdhsa.kernels:
  - .agpr_count:     0
    .args:
      - .offset:         0
        .size:           256
        .value_kind:     by_value
      - .offset:         256
        .size:           4
        .value_kind:     hidden_block_count_x
      - .offset:         260
        .size:           4
        .value_kind:     hidden_block_count_y
      - .offset:         264
        .size:           4
        .value_kind:     hidden_block_count_z
      - .offset:         268
        .size:           2
        .value_kind:     hidden_group_size_x
      - .offset:         270
        .size:           2
        .value_kind:     hidden_group_size_y
      - .offset:         272
        .size:           2
        .value_kind:     hidden_group_size_z
      - .offset:         274
        .size:           2
        .value_kind:     hidden_remainder_x
      - .offset:         276
        .size:           2
        .value_kind:     hidden_remainder_y
      - .offset:         278
        .size:           2
        .value_kind:     hidden_remainder_z
      - .offset:         296
        .size:           8
        .value_kind:     hidden_global_offset_x
      - .offset:         304
        .size:           8
        .value_kind:     hidden_global_offset_y
      - .offset:         312
        .size:           8
        .value_kind:     hidden_global_offset_z
      - .offset:         320
        .size:           2
        .value_kind:     hidden_grid_dims
      - .offset:         344
        .size:           8
        .value_kind:     hidden_multigrid_sync_arg
      - .offset:         376
        .size:           4
        .value_kind:     hidden_dynamic_lds_size
    .group_segment_fixed_size: 0
    .kernarg_segment_align: 8
    .kernarg_segment_size: 512
    .language:       OpenCL C
    .language_version:
      - 2
      - 0
    .max_flat_workgroup_size: 512
    .name:           _Z10hybrid_fwd6Params
    .private_segment_fixed_size: 0
    .sgpr_count:     108
    .sgpr_spill_count: 19
    .symbol:         _Z10hybrid_fwd6Params.kd
    .uniform_work_group_size: 1
    .uses_dynamic_stack: false
    .vgpr_count:     248
    .vgpr_spill_count: 0
    .wavefront_size: 64
